# attention mode 0: P pack runs after the X barrier behind the first V reads, last PV MFMA group runs after the Y barrier behind the next K reads
# baseline (speedup 1.0000x reference)
; __device__ __forceinline__ int v_rd_base(int lane) { return ((lane & 3) << 3) | (((lane >> 2) & 3) << 6) | (((lane >> 4) & 1) << 5) | (((lane >> 5) & 1) << 8); }
; template <int mode> ...
;   asm volatile("" : "+v"(tid));
;   const int wid = __builtin_amdgcn_readfirstlane(tid >> 6), lane = tid & 63, r32 = lane & 31, hi = lane >> 5;
;   const unsigned lds0 = (unsigned)(uintptr_t)lds;
;   float* ws = (float*)(lds + A_LDS_WS) + wid * 64; float* li_l = ws; float* al_l = ws + 32;
;   unsigned koff[2], voff[4];
; #pragma unroll
;   for (int i = 0; i < 2; ++i) { const int row = (wid * 2 + i) * 4 + (lane >> 4), chunk = (lane & 15) ^ (((row & 7) << 1) | ((row >> 3) & 1)); koff[i] = (unsigned)(row * (LDP * 2) + chunk * 16); }
; #pragma unroll
;   for (int i = 0; i < 4; ++i) { const int q = (wid & 3) * 4 + i, subtile = q * 2 + (lane >> 5), kk = (subtile >> 2) * 8 + ((lane & 31) >> 2);
;     const int k = (kk & ~0xC) | ((kk & 4) << 1) | ((kk & 8) >> 1), col = (subtile & 3) * 32 + (lane & 3) * 8;
;     voff[i] = (unsigned)(k * (LDP * 2) + ((wid >> 2) * 128 + col) * 2); }
;   const char* Kb = (const char*)Kh; const char* Vb = (const char*)Vh;
;   const unsigned kdst = lds0 + A_LDS_K + wid * 2048, vdst = lds0 + A_LDS_V + (wid >> 2) * 16384 + (wid & 3) * 4096;
;     ...
;   bf16x8 qr[8];
;   { const hbf* Qw = Qb + (long)(wid * QBLK + r32) * LDQ + hi * 8;
; #pragma unroll
;     for (int d0 = 0; d0 < 8; ++d0) qr[d0] = *reinterpret_cast<const bf16x8*>(Qw + d0 * 16); }
;   asm volatile("" : "+v"(qr[0]), "+v"(qr[1]), "+v"(qr[2]), "+v"(qr[3]), "+v"(qr[4]), "+v"(qr[5]), "+v"(qr[6]), "+v"(qr[7]));
;   DMA_K(0, 0); DMA_V(0, 0); DMA_K(1, 1); DMA_V(1, 1);
;   float m_reg = 0.f, l_reg = 0; f32x16 o[8] = {};
;   const int vb0 = (int)(lds0 + A_LDS_V) + v_rd_base(lane);
;   const int kb0 = (int)(lds0 + A_LDS_K) + r32 * 256, kc = (hi << 4) ^ ((((r32 & 7) << 1) | ((r32 >> 3) & 1)) << 4);
;   const int NT = seq / KVBLK;
;     ...
;   A_WAITBAR(6);
;   if (wid >= 4) asm volatile("s_barrier" ::: "memory");
;   int s0 = 0, s1 = 1, s2 = 2;
;   for (int j = 0; j < NT; ++j) {
;     const bool more = j + 2 < NT;
;     if (more) DMA_K(j + 2, s2);
;     f32x16 p0, p1; bf16x8 pa0, pa1, pa2, pa3;
;     __builtin_amdgcn_s_setprio(2);
;     { f32x16 negm;
; #pragma unroll
;       for (int r = 0; r < 16; ++r) negm[r] = -m_reg;
;       qkt_pipe(p0, p1, kb0 + s0 * 16384, kc, qr, negm); }
.LBB0_347:
	s_and_b32 s8, s8, 0x3fffffc0
	s_lshl_b32 s8, s8, 2
	s_add_i32 s8, s8, 0
	s_add_i32 s8, s8, 0x24000
	s_cmp_lg_u32 0, -1
	s_cselect_b32 s12, 0, 0
	v_lshlrev_b32_e32 v7, 1, v1
	s_and_b32 s10, s10, 7
	v_and_b32_e32 v3, 63, v1
	v_lshl_add_u32 v199, v0, 8, s12
	v_and_b32_e32 v7, 14, v7
	v_bfe_u32 v1, v1, 3, 1
	s_add_i32 s12, s12, 0xc000
	s_lshl_b32 s10, s10, 9
	v_lshlrev_b32_e32 v4, 3, v3
	v_bitop3_b32 v1, v7, v2, v1 bitop3:0x36
	s_add_u32 s10, s38, s10
	v_lshlrev_b32_e32 v200, 4, v3
	v_lshlrev_b32_e32 v6, 1, v3
	v_lshlrev_b32_e32 v213, 4, v1
	v_and_b32_e32 v1, 0x118, v4
	s_addc_u32 s11, s11, 0
	v_and_b32_e32 v5, 0xc0, v200
	v_lshl_add_u32 v201, v0, 2, s8
	v_and_or_b32 v0, v6, 32, v1
	s_add_u32 s60, s14, s10
	v_readlane_b32 s10, v254, 60
	v_mov_b32_e32 v112, v193
	v_mov_b32_e32 v113, v193
	v_cmp_gt_u32_e64 s[40:41], 32, v3
	v_add3_u32 v223, v5, s12, v0
	s_addc_u32 s61, s10, s11
	v_mov_b32_e32 v114, v193
	v_mov_b32_e32 v115, v193
	v_mov_b32_e32 v116, v193
	v_mov_b32_e32 v117, v193
	v_mov_b32_e32 v118, v193
	v_mov_b32_e32 v119, v193
	v_mov_b32_e32 v120, v193
	v_mov_b32_e32 v121, v193
	v_mov_b32_e32 v122, v193
	v_mov_b32_e32 v123, v193
	v_mov_b32_e32 v124, v193
	v_mov_b32_e32 v125, v193
	v_mov_b32_e32 v126, v193
	v_mov_b32_e32 v127, v193
	v_mov_b64_e32 v[96:97], v[112:113]
	v_mov_b64_e32 v[80:81], v[112:113]
	v_mov_b64_e32 v[64:65], v[112:113]
	v_mov_b64_e32 v[48:49], v[112:113]
	v_mov_b64_e32 v[32:33], v[112:113]
	v_mov_b64_e32 v[16:17], v[112:113]
	v_mov_b64_e32 v[0:1], v[112:113]
	s_mov_b32 s9, 2
	s_mov_b32 s29, 1
	s_mov_b32 s24, 0
	v_mov_b32_e32 v224, 0
	s_mov_b64 s[38:39], s[60:61]
	v_mov_b64_e32 v[98:99], v[114:115]
	v_mov_b64_e32 v[100:101], v[116:117]
	v_mov_b64_e32 v[102:103], v[118:119]
	v_mov_b64_e32 v[104:105], v[120:121]
	v_mov_b64_e32 v[106:107], v[122:123]
	v_mov_b64_e32 v[108:109], v[124:125]
	v_mov_b64_e32 v[110:111], v[126:127]
	v_mov_b64_e32 v[82:83], v[114:115]
	v_mov_b64_e32 v[84:85], v[116:117]
	v_mov_b64_e32 v[86:87], v[118:119]
	v_mov_b64_e32 v[88:89], v[120:121]
	v_mov_b64_e32 v[90:91], v[122:123]
	v_mov_b64_e32 v[92:93], v[124:125]
	v_mov_b64_e32 v[94:95], v[126:127]
	v_mov_b64_e32 v[66:67], v[114:115]
	v_mov_b64_e32 v[68:69], v[116:117]
	v_mov_b64_e32 v[70:71], v[118:119]
	v_mov_b64_e32 v[72:73], v[120:121]
	v_mov_b64_e32 v[74:75], v[122:123]
	v_mov_b64_e32 v[76:77], v[124:125]
	v_mov_b64_e32 v[78:79], v[126:127]
	v_mov_b64_e32 v[50:51], v[114:115]
	v_mov_b64_e32 v[52:53], v[116:117]
	v_mov_b64_e32 v[54:55], v[118:119]
	v_mov_b64_e32 v[56:57], v[120:121]
	v_mov_b64_e32 v[58:59], v[122:123]
	v_mov_b64_e32 v[60:61], v[124:125]
	v_mov_b64_e32 v[62:63], v[126:127]
	v_mov_b64_e32 v[34:35], v[114:115]
	v_mov_b64_e32 v[36:37], v[116:117]
	v_mov_b64_e32 v[38:39], v[118:119]
	v_mov_b64_e32 v[40:41], v[120:121]
	v_mov_b64_e32 v[42:43], v[122:123]
	v_mov_b64_e32 v[44:45], v[124:125]
	v_mov_b64_e32 v[46:47], v[126:127]
	v_mov_b64_e32 v[18:19], v[114:115]
	v_mov_b64_e32 v[20:21], v[116:117]
	v_mov_b64_e32 v[22:23], v[118:119]
	v_mov_b64_e32 v[24:25], v[120:121]
	v_mov_b64_e32 v[26:27], v[122:123]
	v_mov_b64_e32 v[28:29], v[124:125]
	v_mov_b64_e32 v[30:31], v[126:127]
	v_mov_b64_e32 v[2:3], v[114:115]
	v_mov_b64_e32 v[4:5], v[116:117]
	v_mov_b64_e32 v[6:7], v[118:119]
	v_mov_b64_e32 v[8:9], v[120:121]
	v_mov_b64_e32 v[10:11], v[122:123]
	v_mov_b64_e32 v[12:13], v[124:125]
	v_mov_b64_e32 v[14:15], v[126:127]
	s_mov_b32 s10, 0
	v_mov_b32_e32 v225, 0
	v_mov_b64_e32 v[128:129], v[114:115]
	v_mov_b64_e32 v[130:131], v[114:115]
	v_mov_b64_e32 v[132:133], v[114:115]
	v_mov_b64_e32 v[134:135], v[114:115]
	v_mov_b64_e32 v[136:137], v[114:115]
	v_mov_b64_e32 v[138:139], v[114:115]
	v_mov_b64_e32 v[140:141], v[114:115]
	v_mov_b64_e32 v[142:143], v[114:115]
	v_mov_b64_e32 v[144:145], v[114:115]
	v_mov_b64_e32 v[146:147], v[114:115]
	v_mov_b64_e32 v[148:149], v[114:115]
	v_mov_b64_e32 v[150:151], v[114:115]
	v_mov_b64_e32 v[152:153], v[114:115]
	v_mov_b64_e32 v[154:155], v[114:115]
	v_mov_b64_e32 v[156:157], v[114:115]
	v_mov_b64_e32 v[158:159], v[114:115]
.LBB0_348:
	s_mov_b32 s11, s24
	s_setprio 2
	v_lshl_add_u32 v212, s11, 14, v199
	v_add_u32_e32 v221, v212, v213
	ds_read_b128 v[194:197], v221 offset:0
	ds_read_b128 v[226:229], v221 offset:0x2000
	v_xor_b32_e32 v221, 32, v213
	v_add_u32_e32 v221, v212, v221
	ds_read_b128 v[230:233], v221 offset:0
	ds_read_b128 v[234:237], v221 offset:0x2000
	v_xor_b32_e32 v221, 64, v213
	v_add_u32_e32 v221, v212, v221
	ds_read_b128 v[238:241], v221 offset:0
	ds_read_b128 v[242:245], v221 offset:0x2000
	v_xor_b32_e32 v221, 0x60, v213
	v_add_u32_e32 v221, v212, v221
	ds_read_b128 v[246:249], v221 offset:0
	ds_read_b128 v[214:217], v221 offset:0x2000
	s_add_i32 s12, s10, 2
	s_cmp_lt_u32 s12, s74
	s_cselect_b64 s[56:57], -1, 0
	s_cmp_ge_u32 s12, s74
	s_cselect_b64 s[90:91], -1, 0
	s_and_b64 vcc, exec, s[90:91]
	v_mfma_f32_32x32x16_bf16 v[0:15], v[128:131], v[144:147], v[0:15]
	v_xor_b32_e32 v128, 0x80000000, v224
	v_mov_b32_e32 v129, v128
	v_mov_b32_e32 v130, v128
	v_mov_b32_e32 v131, v128
	v_mfma_f32_32x32x16_bf16 v[0:15], v[132:135], v[148:151], v[0:15]
	v_mov_b32_e32 v132, v128
	v_mov_b32_e32 v133, v128
	v_mov_b32_e32 v134, v128
	v_mov_b32_e32 v135, v128
	v_mfma_f32_32x32x16_bf16 v[0:15], v[136:139], v[152:155], v[0:15]
	v_mov_b32_e32 v136, v128
	v_mov_b32_e32 v137, v128
	v_mov_b32_e32 v138, v128
	v_mov_b32_e32 v139, v128
	v_mfma_f32_32x32x16_bf16 v[0:15], v[140:143], v[156:159], v[0:15]
	v_mov_b32_e32 v140, v128
	v_mov_b32_e32 v141, v128
	v_mov_b32_e32 v142, v128
	v_mov_b32_e32 v143, v128
	s_waitcnt lgkmcnt(6)
	s_nop 1
	v_mfma_f32_32x32x16_bf16 v[144:159], v[194:197], v[188:191], v[128:143]
	v_mfma_f32_32x32x16_bf16 v[128:143], v[226:229], v[188:191], v[128:143]
	v_xor_b32_e32 v194, 0x80, v213
	v_add_u32_e32 v220, v212, v194
	ds_read_b128 v[194:197], v220 offset:0
	ds_read_b128 v[226:229], v220 offset:0x2000
	s_waitcnt lgkmcnt(6)
	v_mfma_f32_32x32x16_bf16 v[144:159], v[230:233], v[184:187], v[144:159]
	v_mfma_f32_32x32x16_bf16 v[128:143], v[234:237], v[184:187], v[128:143]
	v_xor_b32_e32 v220, 0xa0, v213
	v_add_u32_e32 v220, v212, v220
	ds_read_b128 v[230:233], v220 offset:0
	ds_read_b128 v[234:237], v220 offset:0x2000
	s_cbranch_vccnz .Lq0_nodma
	s_add_u32 s24, s38, 0xfffff000
	s_addc_u32 s25, s39, -1
	s_lshl_b32 s12, s9, 14
	s_add_i32 s12, s12, s0
	s_mov_b32 s13, m0
	s_mov_b32 m0, s12
	s_nop 0
	global_load_lds_dwordx4 v192, s[24:25]
	s_addk_i32 s12, 0x400
	s_mov_b32 m0, s12
	s_nop 0
	global_load_lds_dwordx4 v202, s[24:25]
	s_mov_b32 m0, s13

; #define A_WAITBAR(N) asm volatile("s_waitcnt vmcnt(" #N ") lgkmcnt(0) ; A256BAR\n\ts_barrier" ::: "memory")
; #define DMA_V(t, sl) do { const char* b_ = Vb + (size_t)(t) * TSTRIDE; const unsigned d_ = RFL(vdst + (sl) * 32768); glds16(b_ + voff[0], d_); glds16(b_ + voff[1], d_ + 1024); glds16(b_ + voff[2], d_ + 2048); glds16(b_ + voff[3], d_ + 3072); } while (0)
; #define RESC(a) do { if (__any((a) < 1.f)) { if (hi == 0) al_l[r32] = (a); asm volatile("s_waitcnt lgkmcnt(0)" ::: "memory"); \
;     _Pragma("unroll") for (int d = 0; d < 8; ++d) _Pragma("unroll") for (int r = 0; r < 16; ++r) o[d][r] *= al_l[crow(r, hi)]; } } while (0)
; __device__ __forceinline__ float softmax_rel(f32x16& p0, f32x16& p1, bool first, float& m_reg, float& l_reg, bf16x8& pa0, bf16x8& pa1, bf16x8& pa2, bf16x8& pa3) {
;     ...
; #pragma unroll
;   for (int r = 0; r < 16; ++r) p0[r] = __builtin_amdgcn_exp2f(p0[r]);
; #pragma unroll
;   for (int r = 0; r < 16; ++r) p1[r] = __builtin_amdgcn_exp2f(p1[r]);
;   float ps = 0;
; #pragma unroll
;   for (int r = 0; r < 16; ++r) ps += p0[r];
; #pragma unroll
;   for (int r = 0; r < 16; ++r) ps += p1[r];
;   { auto rr = __builtin_amdgcn_permlane32_swap(__float_as_uint(ps), __float_as_uint(ps), false, false);
;     ps = __uint_as_float(rr[0]) + __uint_as_float(rr[1]); }
;   l_reg = l_reg * alpha + ps;
;   PK4(p0, 0, pa0); PK4(p0, 8, pa1); PK4(p1, 0, pa2); PK4(p1, 8, pa3);
; template <int mode> ...
;     ...
;     const float alpha = softmax_rel(p0, p1, j == 0, m_reg, l_reg, pa0, pa1, pa2, pa3);
;     RESC(alpha);
;     __builtin_amdgcn_s_setprio(0);
;     if (more) A_WAITBAR(6); else A_WAITBAR(0);
;     if (more) DMA_V(j + 2, s2);
;     pv8(o, vb0 + s0 * 32768, pa0, pa1, pa2, pa3);
.LBB0_355:
	v_exp_f32_e32 v144, v144
	v_exp_f32_e32 v145, v145
	v_exp_f32_e32 v146, v146
	v_exp_f32_e32 v147, v147
	v_exp_f32_e32 v148, v148
	v_exp_f32_e32 v194, v128
	v_add_f32_e32 v128, 0, v144
	v_exp_f32_e32 v149, v149
	v_add_f32_e32 v128, v145, v128
	v_exp_f32_e32 v150, v150
	v_add_f32_e32 v128, v146, v128
	v_exp_f32_e32 v151, v151
	v_add_f32_e32 v128, v147, v128
	v_exp_f32_e32 v152, v152
	v_add_f32_e32 v128, v148, v128
	v_exp_f32_e32 v153, v153
	v_add_f32_e32 v128, v149, v128
	v_exp_f32_e32 v154, v154
	v_add_f32_e32 v128, v150, v128
	v_exp_f32_e32 v155, v155
	v_add_f32_e32 v128, v151, v128
	v_exp_f32_e32 v156, v156
	v_add_f32_e32 v128, v152, v128
	v_exp_f32_e32 v157, v157
	v_add_f32_e32 v128, v153, v128
	v_exp_f32_e32 v158, v158
	v_add_f32_e32 v128, v154, v128
	v_exp_f32_e32 v159, v159
	v_add_f32_e32 v128, v155, v128
	v_add_f32_e32 v128, v156, v128
	v_exp_f32_e32 v195, v129
	v_add_f32_e32 v128, v157, v128
	v_exp_f32_e32 v196, v130
	v_add_f32_e32 v128, v158, v128
	v_exp_f32_e32 v197, v131
	v_add_f32_e32 v128, v159, v128
	v_exp_f32_e32 v214, v132
	v_add_f32_e32 v128, v194, v128
	v_exp_f32_e32 v215, v133
	v_add_f32_e32 v128, v195, v128
	v_exp_f32_e32 v216, v134
	v_add_f32_e32 v128, v196, v128
	v_exp_f32_e32 v217, v135
	v_add_f32_e32 v128, v197, v128
	v_exp_f32_e32 v220, v136
	v_add_f32_e32 v128, v214, v128
	v_exp_f32_e32 v221, v137
	v_add_f32_e32 v128, v215, v128
	v_exp_f32_e32 v222, v138
	v_add_f32_e32 v128, v216, v128
	v_exp_f32_e32 v228, v139
	v_add_f32_e32 v128, v217, v128
	v_exp_f32_e32 v229, v140
	v_add_f32_e32 v128, v220, v128
	v_exp_f32_e32 v230, v141
	v_add_f32_e32 v128, v221, v128
	v_exp_f32_e32 v231, v142
	v_add_f32_e32 v128, v222, v128
	v_exp_f32_e32 v143, v143
	v_add_f32_e32 v128, v228, v128
	v_add_f32_e32 v128, v229, v128
	v_add_f32_e32 v128, v230, v128
	v_add_f32_e32 v128, v231, v128
	v_add_f32_e32 v212, v143, v128
	v_mov_b32_e32 v227, v212
.LBB0_359:
	s_setprio 0
	s_and_b64 vcc, exec, s[90:91]
	s_cbranch_vccnz .Lp0_bar0
	s_waitcnt vmcnt(6) lgkmcnt(0)
	s_barrier
.LBB0_363:
	v_lshl_add_u32 v128, s11, 15, v223
	ds_read_b64_tr_b16 v[232:233], v128 offset:0
	ds_read_b64_tr_b16 v[234:235], v128 offset:0x800
	ds_read_b64_tr_b16 v[236:237], v128 offset:0x1000
	ds_read_b64_tr_b16 v[238:239], v128 offset:0x1800
	ds_read_b64_tr_b16 v[240:241], v128 offset:0x2000
	ds_read_b64_tr_b16 v[242:243], v128 offset:0x2800
	ds_read_b64_tr_b16 v[244:245], v128 offset:0x3000
	ds_read_b64_tr_b16 v[246:247], v128 offset:0x3800
	v_cvt_pk_bf16_f32 v128, v144, v145
	v_cvt_pk_bf16_f32 v129, v146, v147
	v_cvt_pk_bf16_f32 v130, v148, v149
	v_cvt_pk_bf16_f32 v131, v150, v151
	v_cvt_pk_bf16_f32 v132, v152, v153
	v_cvt_pk_bf16_f32 v133, v154, v155
	v_cvt_pk_bf16_f32 v134, v156, v157
	v_cvt_pk_bf16_f32 v135, v158, v159
	v_cvt_pk_bf16_f32 v136, v194, v195
	v_cvt_pk_bf16_f32 v137, v196, v197
	v_cvt_pk_bf16_f32 v138, v214, v215
	v_cvt_pk_bf16_f32 v139, v216, v217
	v_cvt_pk_bf16_f32 v140, v220, v221
	v_cvt_pk_bf16_f32 v141, v222, v228
	v_cvt_pk_bf16_f32 v142, v229, v230
	v_cvt_pk_bf16_f32 v143, v231, v143
	s_nop 1
	v_permlane32_swap_b32_e32 v212, v227
	v_cmp_gt_f32_e32 vcc, 1.0, v226
	s_cbranch_vccnz .Lm0_resc
.Lx0_back:
	v_lshl_add_u32 v220, s11, 15, v223
	ds_read_b64_tr_b16 v[144:145], v220 offset:0x200
	ds_read_b64_tr_b16 v[146:147], v220 offset:0xa00
	ds_read_b64_tr_b16 v[148:149], v220 offset:0x1200
	ds_read_b64_tr_b16 v[150:151], v220 offset:0x1a00
	ds_read_b64_tr_b16 v[152:153], v220 offset:0x2200
	ds_read_b64_tr_b16 v[154:155], v220 offset:0x2a00
	ds_read_b64_tr_b16 v[156:157], v220 offset:0x3200
	ds_read_b64_tr_b16 v[158:159], v220 offset:0x3a00
	s_waitcnt lgkmcnt(8)
	v_add_u32_e32 v221, 0x4000, v220
	v_mfma_f32_32x32x16_bf16 v[112:127], v[128:131], v[232:235], v[112:127]
	v_mfma_f32_32x32x16_bf16 v[112:127], v[132:135], v[236:239], v[112:127]
	v_mfma_f32_32x32x16_bf16 v[112:127], v[136:139], v[240:243], v[112:127]
	v_mfma_f32_32x32x16_bf16 v[112:127], v[140:143], v[244:247], v[112:127]
	ds_read_b64_tr_b16 v[232:233], v220 offset:0x400
	ds_read_b64_tr_b16 v[234:235], v220 offset:0xc00
	ds_read_b64_tr_b16 v[236:237], v220 offset:0x1400
	ds_read_b64_tr_b16 v[238:239], v220 offset:0x1c00
	ds_read_b64_tr_b16 v[240:241], v220 offset:0x2400
	ds_read_b64_tr_b16 v[242:243], v220 offset:0x2c00
	ds_read_b64_tr_b16 v[244:245], v220 offset:0x3400
	ds_read_b64_tr_b16 v[246:247], v220 offset:0x3c00
	s_waitcnt lgkmcnt(8)
	v_mfma_f32_32x32x16_bf16 v[96:111], v[128:131], v[144:147], v[96:111]
	v_mfma_f32_32x32x16_bf16 v[96:111], v[132:135], v[148:151], v[96:111]
	v_mfma_f32_32x32x16_bf16 v[96:111], v[136:139], v[152:155], v[96:111]
	v_mfma_f32_32x32x16_bf16 v[96:111], v[140:143], v[156:159], v[96:111]
	ds_read_b64_tr_b16 v[144:145], v220 offset:0x600
	ds_read_b64_tr_b16 v[146:147], v220 offset:0xe00
	ds_read_b64_tr_b16 v[148:149], v220 offset:0x1600
	ds_read_b64_tr_b16 v[150:151], v220 offset:0x1e00
	ds_read_b64_tr_b16 v[152:153], v220 offset:0x2600
	ds_read_b64_tr_b16 v[154:155], v220 offset:0x2e00
	ds_read_b64_tr_b16 v[156:157], v220 offset:0x3600
	ds_read_b64_tr_b16 v[158:159], v220 offset:0x3e00
	s_and_b64 vcc, exec, s[90:91]
	s_cbranch_vccnz .Lp0_nodma
	s_lshl_b32 s12, s9, 15
	s_add_i32 s12, s12, s7
	s_mov_b32 s13, m0
	s_mov_b32 m0, s12
	s_nop 0
	global_load_lds_dwordx4 v204, s[38:39]
	s_add_i32 s24, s12, 0x400
	s_mov_b32 m0, s24
	s_nop 0
	global_load_lds_dwordx4 v206, s[38:39]
	s_add_i32 s24, s12, 0x800
	s_mov_b32 m0, s24
	s_nop 0
	global_load_lds_dwordx4 v208, s[38:39]
	s_add_i32 s24, s12, 0xc00
	s_mov_b32 m0, s24
	s_nop 0
	global_load_lds_dwordx4 v210, s[38:39]
	s_mov_b32 m0, s13
; #define SBAR() __builtin_amdgcn_sched_barrier(0)
; #define VF_WAIT(N) do { asm volatile("s_waitcnt lgkmcnt(" #N ")" ::: "memory"); SBAR(); } while (0)
; #define A_WAITBAR(N) asm volatile("s_waitcnt vmcnt(" #N ") lgkmcnt(0) ; A256BAR\n\ts_barrier" ::: "memory")
; __device__ __forceinline__ void pv8(f32x16* o, int vb, bf16x8 pa0, bf16x8 pa1, bf16x8 pa2, bf16x8 pa3) {
;   VFrag fa, fb; const int vb2 = vb + 16384;
;   vf_read<0>(fa, vb);
;   vf_read<1>(fb, vb);  VF_WAIT(8); vf_mma(o[0], fa, pa0, pa1, pa2, pa3); SBAR();
;   vf_read<2>(fa, vb);  VF_WAIT(8); vf_mma(o[1], fb, pa0, pa1, pa2, pa3); SBAR();
;   vf_read<3>(fb, vb);  VF_WAIT(8); vf_mma(o[2], fa, pa0, pa1, pa2, pa3); SBAR();
;   vf_read<0>(fa, vb2); VF_WAIT(8); vf_mma(o[3], fb, pa0, pa1, pa2, pa3); SBAR();
;   vf_read<1>(fb, vb2); VF_WAIT(8); vf_mma(o[4], fa, pa0, pa1, pa2, pa3); SBAR();
;   vf_read<2>(fa, vb2); VF_WAIT(8); vf_mma(o[5], fb, pa0, pa1, pa2, pa3); SBAR();
;   vf_read<3>(fb, vb2); VF_WAIT(8); vf_mma(o[6], fa, pa0, pa1, pa2, pa3); SBAR();
;   VF_WAIT(0); vf_mma(o[7], fb, pa0, pa1, pa2, pa3);
; }
; template <int mode> ...
;     ...
;     if (more) A_WAITBAR(6); else A_WAITBAR(0);
;     { const int t_ = s0; s0 = s1; s1 = s2; s2 = t_; }
;   }
.Lp0_nodma:
	s_waitcnt lgkmcnt(8)
	v_mfma_f32_32x32x16_bf16 v[80:95], v[128:131], v[232:235], v[80:95]
	v_mfma_f32_32x32x16_bf16 v[80:95], v[132:135], v[236:239], v[80:95]
	v_mfma_f32_32x32x16_bf16 v[80:95], v[136:139], v[240:243], v[80:95]
	v_mfma_f32_32x32x16_bf16 v[80:95], v[140:143], v[244:247], v[80:95]
	ds_read_b64_tr_b16 v[232:233], v221 offset:0
	ds_read_b64_tr_b16 v[234:235], v221 offset:0x800
	ds_read_b64_tr_b16 v[236:237], v221 offset:0x1000
	ds_read_b64_tr_b16 v[238:239], v221 offset:0x1800
	ds_read_b64_tr_b16 v[240:241], v221 offset:0x2000
	ds_read_b64_tr_b16 v[242:243], v221 offset:0x2800
	ds_read_b64_tr_b16 v[244:245], v221 offset:0x3000
	ds_read_b64_tr_b16 v[246:247], v221 offset:0x3800
	s_waitcnt lgkmcnt(8)
	v_mfma_f32_32x32x16_bf16 v[64:79], v[128:131], v[144:147], v[64:79]
	v_mfma_f32_32x32x16_bf16 v[64:79], v[132:135], v[148:151], v[64:79]
	v_mfma_f32_32x32x16_bf16 v[64:79], v[136:139], v[152:155], v[64:79]
	v_mfma_f32_32x32x16_bf16 v[64:79], v[140:143], v[156:159], v[64:79]
	ds_read_b64_tr_b16 v[144:145], v221 offset:0x200
	ds_read_b64_tr_b16 v[146:147], v221 offset:0xa00
	ds_read_b64_tr_b16 v[148:149], v221 offset:0x1200
	ds_read_b64_tr_b16 v[150:151], v221 offset:0x1a00
	ds_read_b64_tr_b16 v[152:153], v221 offset:0x2200
	ds_read_b64_tr_b16 v[154:155], v221 offset:0x2a00
	ds_read_b64_tr_b16 v[156:157], v221 offset:0x3200
	ds_read_b64_tr_b16 v[158:159], v221 offset:0x3a00
	s_waitcnt lgkmcnt(8)
	v_mfma_f32_32x32x16_bf16 v[48:63], v[128:131], v[232:235], v[48:63]
	v_mfma_f32_32x32x16_bf16 v[48:63], v[132:135], v[236:239], v[48:63]
	v_mfma_f32_32x32x16_bf16 v[48:63], v[136:139], v[240:243], v[48:63]
	v_mfma_f32_32x32x16_bf16 v[48:63], v[140:143], v[244:247], v[48:63]
	ds_read_b64_tr_b16 v[232:233], v221 offset:0x400
	ds_read_b64_tr_b16 v[234:235], v221 offset:0xc00
	ds_read_b64_tr_b16 v[236:237], v221 offset:0x1400
	ds_read_b64_tr_b16 v[238:239], v221 offset:0x1c00
	ds_read_b64_tr_b16 v[240:241], v221 offset:0x2400
	ds_read_b64_tr_b16 v[242:243], v221 offset:0x2c00
	ds_read_b64_tr_b16 v[244:245], v221 offset:0x3400
	ds_read_b64_tr_b16 v[246:247], v221 offset:0x3c00
	s_waitcnt lgkmcnt(8)
	v_mfma_f32_32x32x16_bf16 v[32:47], v[128:131], v[144:147], v[32:47]
	v_mfma_f32_32x32x16_bf16 v[32:47], v[132:135], v[148:151], v[32:47]
	v_mfma_f32_32x32x16_bf16 v[32:47], v[136:139], v[152:155], v[32:47]
	v_mfma_f32_32x32x16_bf16 v[32:47], v[140:143], v[156:159], v[32:47]
	ds_read_b64_tr_b16 v[144:145], v221 offset:0x600
	ds_read_b64_tr_b16 v[146:147], v221 offset:0xe00
	ds_read_b64_tr_b16 v[148:149], v221 offset:0x1600
	ds_read_b64_tr_b16 v[150:151], v221 offset:0x1e00
	ds_read_b64_tr_b16 v[152:153], v221 offset:0x2600
	ds_read_b64_tr_b16 v[154:155], v221 offset:0x2e00
	ds_read_b64_tr_b16 v[156:157], v221 offset:0x3600
	ds_read_b64_tr_b16 v[158:159], v221 offset:0x3e00
	s_waitcnt lgkmcnt(8)
	v_mfma_f32_32x32x16_bf16 v[16:31], v[128:131], v[232:235], v[16:31]
	v_mfma_f32_32x32x16_bf16 v[16:31], v[132:135], v[236:239], v[16:31]
	v_mfma_f32_32x32x16_bf16 v[16:31], v[136:139], v[240:243], v[16:31]
	v_mfma_f32_32x32x16_bf16 v[16:31], v[140:143], v[244:247], v[16:31]
	s_waitcnt lgkmcnt(0)
	s_and_b64 vcc, exec, s[90:91]
	s_cbranch_vccnz .Lm0_ybar0
	s_waitcnt vmcnt(6) lgkmcnt(0)
	s_barrier
.LBB0_367:
	s_add_i32 s10, s10, 1
	s_add_u32 s38, s38, 0x180000
	s_addc_u32 s39, s39, 0
	s_cmp_eq_u32 s74, s10
	s_cbranch_scc1 .Lm0_fin
	v_add_f32_e32 v220, v212, v227
	v_fmac_f32_e32 v220, v225, v226
	v_mov_b32_e32 v225, v220
	s_mov_b32 s24, s29
	s_mov_b32 s29, s9
	s_mov_b32 s9, s11
	s_branch .LBB0_348
.Lm0_fin:
	v_mfma_f32_32x32x16_bf16 v[0:15], v[128:131], v[144:147], v[0:15]
	v_mfma_f32_32x32x16_bf16 v[0:15], v[132:135], v[148:151], v[0:15]
	v_mfma_f32_32x32x16_bf16 v[0:15], v[136:139], v[152:155], v[0:15]
	v_mfma_f32_32x32x16_bf16 v[0:15], v[140:143], v[156:159], v[0:15]
	v_add_f32_e32 v128, v212, v227
	v_fmac_f32_e32 v128, v225, v226
	s_nop 7
	s_nop 7
	s_branch .LBB0_374
